# in-proj epilogue passes: the 8 staged-row LDS reads issued together, store addresses computed ahead, stores with counted waits
# baseline (speedup 1.0000x reference)
; DI unsigned pk2(float lo, float hi) { unsigned r; asm volatile("v_cvt_pk_bf16_f32 %0, %1, %2" : "=v"(r) : "v"(lo), "v"(hi)); return r; }
; template <int MODE>
; DI void gemm_phase(const Params& p, int layer, int hf, unsigned char* shmc, int tid) {
;     ...
; #pragma unroll
;         for (int ai = 0; ai < 2; ++ai) {
; #pragma unroll
;           for (int m = 0; m < 4; ++m) {
;             unsigned char* rp = es + (wr * 64 + m * 16 + fr) * 528 + (wc * 32 + fq * 4) * 2;
; #pragma unroll
;             for (int bj = 0; bj < 2; ++bj)
; #pragma unroll
;               for (int n = 0; n < 2; ++n) { const f32x4 v = acc[ai][bj][m][n]; uint2 w; w.x = pk2(v[0], v[1]); w.y = pk2(v[2], v[3]); *(uint2*)(rp + (bj * HALF + n * 16) * 2) = w; }
;           }
;           __syncthreads();
;           {
;             const int r0 = tid >> 5, ch = tid & 31;
; #pragma unroll
;             for (int i = 0; i < 8; ++i) {
;               const int row = r0 + 16 * i;
;               { typedef unsigned u32x4_t __attribute__((ext_vector_type(4))); const u32x4_t v_ = *(const u32x4_t*)(es + row * 528 + ch * 16); __builtin_nontemporal_store(v_, (u32x4_t*)(proj + (size_t)(brow + ai * HALF + row) * NP + bcol + ch * 8)); }
;             }
;           }
;           __syncthreads();
;         }
.Lg0_nopre:
	v_cvt_pk_bf16_f32 v124, v124, v125
	v_cvt_pk_bf16_f32 v125, v126, v127
	ds_write_b64 v189, v[124:125]
	v_cvt_pk_bf16_f32 v120, v120, v121
	v_cvt_pk_bf16_f32 v121, v122, v123
	ds_write_b64 v189, v[120:121] offset:32
	v_cvt_pk_bf16_f32 v112, v112, v113
	v_cvt_pk_bf16_f32 v113, v114, v115
	ds_write_b64 v189, v[112:113] offset:256
	v_cvt_pk_bf16_f32 v104, v104, v105
	v_cvt_pk_bf16_f32 v105, v106, v107
	ds_write_b64 v189, v[104:105] offset:288
	v_cvt_pk_bf16_f32 v104, v116, v117
	v_cvt_pk_bf16_f32 v105, v118, v119
	ds_write_b64 v189, v[104:105] offset:8448
	v_cvt_pk_bf16_f32 v104, v108, v109
	v_cvt_pk_bf16_f32 v105, v110, v111
	ds_write_b64 v189, v[104:105] offset:8480
	v_cvt_pk_bf16_f32 v96, v96, v97
	v_cvt_pk_bf16_f32 v97, v98, v99
	ds_write_b64 v189, v[96:97] offset:8704
	v_cvt_pk_bf16_f32 v88, v88, v89
	v_cvt_pk_bf16_f32 v89, v90, v91
	ds_write_b64 v189, v[88:89] offset:8736
	v_cvt_pk_bf16_f32 v88, v100, v101
	v_cvt_pk_bf16_f32 v89, v102, v103
	ds_write_b64 v189, v[88:89] offset:16896
	v_cvt_pk_bf16_f32 v88, v92, v93
	v_cvt_pk_bf16_f32 v89, v94, v95
	ds_write_b64 v189, v[88:89] offset:16928
	v_cvt_pk_bf16_f32 v80, v80, v81
	v_cvt_pk_bf16_f32 v81, v82, v83
	ds_write_b64 v189, v[80:81] offset:17152
	v_cvt_pk_bf16_f32 v72, v72, v73
	v_cvt_pk_bf16_f32 v73, v74, v75
	ds_write_b64 v189, v[72:73] offset:17184
	v_cvt_pk_bf16_f32 v72, v84, v85
	v_cvt_pk_bf16_f32 v73, v86, v87
	s_lshl_b32 s10, s26, 8
	ds_write_b64 v189, v[72:73] offset:25344
	v_cvt_pk_bf16_f32 v72, v76, v77
	v_cvt_pk_bf16_f32 v73, v78, v79
	ds_write_b64 v189, v[72:73] offset:25376
	v_cvt_pk_bf16_f32 v68, v68, v69
	v_cvt_pk_bf16_f32 v69, v70, v71
	ds_write_b64 v189, v[68:69] offset:25600
	v_cvt_pk_bf16_f32 v56, v56, v57
	v_cvt_pk_bf16_f32 v57, v58, v59
	s_ashr_i32 s11, s10, 31
	ds_write_b64 v189, v[56:57] offset:25632
	s_waitcnt lgkmcnt(0)
	s_barrier
	ds_read_b128 v[204:207], v190
	ds_read_b128 v[208:211], v190 offset:8448
	ds_read_b128 v[212:215], v190 offset:16896
	ds_read_b128 v[216:219], v190 offset:25344
	ds_read_b128 v[220:223], v190 offset:33792
	ds_read_b128 v[224:227], v190 offset:42240
	ds_read_b128 v[228:231], v190 offset:50688
	ds_read_b128 v[232:235], v190 offset:59136
	v_lshl_add_u64 v[128:129], s[10:11], 1, v[174:175]
	v_add_u32_e32 v236, s18, v180
	v_mad_i64_i32 v[236:237], s[10:11], v236, s65, v[128:129]
	v_add_u32_e32 v238, s18, v181
	v_mad_i64_i32 v[238:239], s[10:11], v238, s65, v[128:129]
	v_add_u32_e32 v240, s18, v182
	v_mad_i64_i32 v[240:241], s[10:11], v240, s65, v[128:129]
	v_add_u32_e32 v242, s18, v183
	v_mad_i64_i32 v[242:243], s[10:11], v242, s65, v[128:129]
	v_add_u32_e32 v244, s18, v184
	v_mad_i64_i32 v[244:245], s[10:11], v244, s65, v[128:129]
	v_add_u32_e32 v246, s18, v185
	v_mad_i64_i32 v[246:247], s[10:11], v246, s65, v[128:129]
	v_add_u32_e32 v248, s18, v186
	v_mad_i64_i32 v[248:249], s[10:11], v248, s65, v[128:129]
	v_add_u32_e32 v250, s18, v187
	v_mad_i64_i32 v[250:251], s[10:11], v250, s65, v[128:129]
	s_waitcnt lgkmcnt(7)
	global_store_dwordx4 v[236:237], v[204:207], off nt
	s_waitcnt lgkmcnt(6)
	global_store_dwordx4 v[238:239], v[208:211], off nt
	s_waitcnt lgkmcnt(5)
	global_store_dwordx4 v[240:241], v[212:215], off nt
	s_waitcnt lgkmcnt(4)
	global_store_dwordx4 v[242:243], v[216:219], off nt
	s_waitcnt lgkmcnt(3)
	global_store_dwordx4 v[244:245], v[220:223], off nt
	s_waitcnt lgkmcnt(2)
	global_store_dwordx4 v[246:247], v[224:227], off nt
	s_waitcnt lgkmcnt(1)
	global_store_dwordx4 v[248:249], v[228:231], off nt
	s_waitcnt lgkmcnt(0)
	global_store_dwordx4 v[250:251], v[232:235], off nt
	s_barrier
	v_cvt_pk_bf16_f32 v36, v36, v37
	v_cvt_pk_bf16_f32 v37, v38, v39
	ds_write_b64 v189, v[36:37]
	v_cvt_pk_bf16_f32 v24, v24, v25
	v_cvt_pk_bf16_f32 v25, v26, v27
	ds_write_b64 v189, v[24:25] offset:32
	v_cvt_pk_bf16_f32 v24, v64, v65
	v_cvt_pk_bf16_f32 v25, v66, v67
	ds_write_b64 v189, v[24:25] offset:256
	v_cvt_pk_bf16_f32 v24, v60, v61
	v_cvt_pk_bf16_f32 v25, v62, v63
	ds_write_b64 v189, v[24:25] offset:288
	v_cvt_pk_bf16_f32 v4, v4, v5
	v_cvt_pk_bf16_f32 v5, v6, v7
	ds_write_b64 v189, v[4:5] offset:8448
	v_cvt_pk_bf16_f32 v0, v0, v1
	v_cvt_pk_bf16_f32 v1, v2, v3
	ds_write_b64 v189, v[0:1] offset:8480
	v_cvt_pk_bf16_f32 v0, v52, v53
	v_cvt_pk_bf16_f32 v1, v54, v55
	ds_write_b64 v189, v[0:1] offset:8704
	v_cvt_pk_bf16_f32 v0, v48, v49
	v_cvt_pk_bf16_f32 v1, v50, v51
	ds_write_b64 v189, v[0:1] offset:8736
	v_cvt_pk_bf16_f32 v0, v32, v33
	v_cvt_pk_bf16_f32 v1, v34, v35
	ds_write_b64 v189, v[0:1] offset:16896
	v_cvt_pk_bf16_f32 v0, v28, v29
	v_cvt_pk_bf16_f32 v1, v30, v31
	ds_write_b64 v189, v[0:1] offset:16928
	v_cvt_pk_bf16_f32 v0, v44, v45
	v_cvt_pk_bf16_f32 v1, v46, v47
	ds_write_b64 v189, v[0:1] offset:17152
	v_cvt_pk_bf16_f32 v0, v40, v41
	v_cvt_pk_bf16_f32 v1, v42, v43
	ds_write_b64 v189, v[0:1] offset:17184
	v_cvt_pk_bf16_f32 v0, v12, v13
	v_cvt_pk_bf16_f32 v1, v14, v15
	ds_write_b64 v189, v[0:1] offset:25344
	v_cvt_pk_bf16_f32 v0, v8, v9
	v_cvt_pk_bf16_f32 v1, v10, v11
	ds_write_b64 v189, v[0:1] offset:25376
	v_cvt_pk_bf16_f32 v0, v20, v21
	v_cvt_pk_bf16_f32 v1, v22, v23
	ds_write_b64 v189, v[0:1] offset:25600
	v_cvt_pk_bf16_f32 v0, v16, v17
	v_cvt_pk_bf16_f32 v1, v18, v19
	ds_write_b64 v189, v[0:1] offset:25632
	s_waitcnt lgkmcnt(0)
	s_barrier
	s_bitset1_b32 s18, 7
	ds_read_b128 v[204:207], v190
	ds_read_b128 v[208:211], v190 offset:8448
	ds_read_b128 v[212:215], v190 offset:16896
	ds_read_b128 v[216:219], v190 offset:25344
	ds_read_b128 v[220:223], v190 offset:33792
	ds_read_b128 v[224:227], v190 offset:42240
	ds_read_b128 v[228:231], v190 offset:50688
	ds_read_b128 v[232:235], v190 offset:59136
	v_add_u32_e32 v236, s18, v180
	v_mad_i64_i32 v[236:237], s[10:11], v236, s65, v[128:129]
	v_add_u32_e32 v238, s18, v181
	v_mad_i64_i32 v[238:239], s[10:11], v238, s65, v[128:129]
	v_add_u32_e32 v240, s18, v182
	v_mad_i64_i32 v[240:241], s[10:11], v240, s65, v[128:129]
	v_add_u32_e32 v242, s18, v183
	v_mad_i64_i32 v[242:243], s[10:11], v242, s65, v[128:129]
	v_add_u32_e32 v244, s18, v184
	v_mad_i64_i32 v[244:245], s[10:11], v244, s65, v[128:129]
	v_add_u32_e32 v246, s18, v185
	v_mad_i64_i32 v[246:247], s[10:11], v246, s65, v[128:129]
	v_add_u32_e32 v248, s18, v186
	v_mad_i64_i32 v[248:249], s[10:11], v248, s65, v[128:129]
	v_add_u32_e32 v250, s18, v187
	v_mad_i64_i32 v[250:251], s[10:11], v250, s65, v[128:129]
	s_waitcnt lgkmcnt(7)
	global_store_dwordx4 v[236:237], v[204:207], off nt
	s_waitcnt lgkmcnt(6)
	global_store_dwordx4 v[238:239], v[208:211], off nt
	s_waitcnt lgkmcnt(5)
	global_store_dwordx4 v[240:241], v[212:215], off nt
	s_waitcnt lgkmcnt(4)
	global_store_dwordx4 v[242:243], v[216:219], off nt
	s_waitcnt lgkmcnt(3)
	global_store_dwordx4 v[244:245], v[220:223], off nt
	s_waitcnt lgkmcnt(2)
	global_store_dwordx4 v[246:247], v[224:227], off nt
	s_waitcnt lgkmcnt(1)
	global_store_dwordx4 v[248:249], v[228:231], off nt
	s_waitcnt lgkmcnt(0)
	global_store_dwordx4 v[250:251], v[232:235], off nt
	s_barrier
	s_branch .LBB0_153
